# speedup vs baseline: 1.0223x; 1.0223x over previous
; DEVI float bfs(short h) { return __uint_as_float(((unsigned)(u16)h) << 16); }
; DEVI float sigm_f(float x) { return 1.f / (1.f + __expf(-x)); }
; DEVI void gemm256(const P& p, const u16* A, int lda, const u16* Bt, int ldb, int K, int brow, int bcol, int mode,
;                         int aux, int layer, int bmode) {
;     ...
;     for (int it = 0; it < 4; ++it) {
;       const int R = it * 64 + (tid >> 3), co = tid & 7;
;       const int row = brow + R, ocol = bcol + co * 8;
;       float sum[8] = {0, 0, 0, 0, 0, 0, 0, 0};
; #pragma unroll
;       for (int br = 0; br < 4; ++br) {
;         const int c = br * 8 + co;
;         bf16x8 g = *(const bf16x8*)(stg + R * 256 + SWZ(R, c) * 8);
;         float yb[8];
;         ld8((const u16*)(ws + O_YBR) + (size_t)row * 8192 + br * 2048 + ocol, yb);
; #pragma unroll
;         for (int e = 0; e < 8; ++e) sum[e] += (br == PROBE_ZB) ? 0.f : sigm_f(bfs(g[e])) * yb[e];
;       }
;       st8((u16*)(ws + O_ACC) + (size_t)row * 2048 + ocol, sum);
;     }
.LBB0_315:
	v_lshl_add_u64 v[10:11], v[18:19], 0, v[14:15]
	v_add_co_u32_e32 v2, vcc, 0xa28a000, v10
	v_add_u32_e32 v6, s2, v62
	s_nop 0
	v_addc_co_u32_e32 v3, vcc, 0, v11, vcc
	global_load_dwordx4 v[2:5], v[2:3], off
	v_add_u32_e32 v40, s2, v60
	v_add_co_u32_e32 v12, vcc, s6, v10
	s_mov_b32 s3, 0xa28d000
	s_nop 0
	v_addc_co_u32_e32 v13, vcc, 0, v11, vcc
	v_add_co_u32_e32 v10, vcc, s3, v10
	ds_read_b128 v[44:47], v40
	s_nop 0
	v_addc_co_u32_e32 v11, vcc, 0, v11, vcc
	s_waitcnt vmcnt(0)
	v_and_b32_e32 v35, 0xffff0000, v2
	v_lshlrev_b32_e32 v34, 16, v2
	v_and_b32_e32 v29, 0xffff0000, v3
	v_lshlrev_b32_e32 v28, 16, v3
	v_and_b32_e32 v25, 0xffff0000, v4
	v_lshlrev_b32_e32 v24, 16, v4
	v_and_b32_e32 v21, 0xffff0000, v5
	v_lshlrev_b32_e32 v20, 16, v5
	ds_read_b128 v[2:5], v6
	s_waitcnt lgkmcnt(0)
	v_lshlrev_b32_e32 v6, 16, v2
	v_and_b32_e32 v2, 0xffff0000, v2
	v_mul_f32_e32 v2, 0xbfb8aa3b, v2
	v_exp_f32_e32 v7, v2
	v_lshlrev_b32_e32 v2, 16, v3
	v_and_b32_e32 v3, 0xffff0000, v3
	v_mul_f32_e32 v2, 0xbfb8aa3b, v2
	v_mul_f32_e32 v3, 0xbfb8aa3b, v3
	v_exp_f32_e32 v2, v2
	v_exp_f32_e32 v3, v3
	v_mul_f32_e32 v6, 0xbfb8aa3b, v6
	v_exp_f32_e32 v6, v6
	v_pk_add_f32 v[32:33], v[2:3], 1.0 op_sel_hi:[1,0]
	v_lshlrev_b32_e32 v2, 16, v4
	v_and_b32_e32 v3, 0xffff0000, v4
	v_mul_f32_e32 v2, 0xbfb8aa3b, v2
	v_mul_f32_e32 v3, 0xbfb8aa3b, v3
	v_exp_f32_e32 v2, v2
	v_exp_f32_e32 v3, v3
	v_pk_add_f32 v[38:39], v[6:7], 1.0 op_sel_hi:[1,0]
	v_add_u32_e32 v6, s2, v61
	ds_read_b128 v[6:9], v6
	v_pk_add_f32 v[26:27], v[2:3], 1.0 op_sel_hi:[1,0]
	v_lshlrev_b32_e32 v2, 16, v5
	v_and_b32_e32 v3, 0xffff0000, v5
	v_mul_f32_e32 v2, 0xbfb8aa3b, v2
	v_mul_f32_e32 v3, 0xbfb8aa3b, v3
	v_exp_f32_e32 v2, v2
	v_exp_f32_e32 v3, v3
	s_waitcnt lgkmcnt(0)
	v_lshlrev_b32_e32 v30, 16, v6
	v_and_b32_e32 v6, 0xffff0000, v6
	v_mul_f32_e32 v6, 0xbfb8aa3b, v6
	v_pk_add_f32 v[22:23], v[2:3], 1.0 op_sel_hi:[1,0]
	global_load_dwordx4 v[2:5], v[12:13], off offset:-4096
	v_exp_f32_e32 v51, v6
	v_lshlrev_b32_e32 v6, 16, v7
	v_mul_f32_e32 v6, 0xbfb8aa3b, v6
	v_exp_f32_e32 v42, v6
	v_and_b32_e32 v6, 0xffff0000, v7
	v_mul_f32_e32 v6, 0xbfb8aa3b, v6
	v_exp_f32_e32 v43, v6
	v_lshlrev_b32_e32 v6, 16, v8
	v_mul_f32_e32 v6, 0xbfb8aa3b, v6
	v_exp_f32_e32 v36, v6
	v_and_b32_e32 v6, 0xffff0000, v8
	v_mul_f32_e32 v6, 0xbfb8aa3b, v6
	v_exp_f32_e32 v37, v6
	v_lshlrev_b32_e32 v6, 16, v9
	v_mul_f32_e32 v30, 0xbfb8aa3b, v30
	v_mul_f32_e32 v6, 0xbfb8aa3b, v6
	v_exp_f32_e32 v50, v30
	v_exp_f32_e32 v30, v6
	v_and_b32_e32 v6, 0xffff0000, v9
	v_mul_f32_e32 v6, 0xbfb8aa3b, v6
	v_exp_f32_e32 v31, v6
	global_load_dwordx4 v[6:9], v[12:13], off
	v_lshlrev_b32_e32 v12, 16, v44
	v_mul_f32_e32 v12, 0xbfb8aa3b, v12
	v_exp_f32_e32 v56, v12
	v_and_b32_e32 v12, 0xffff0000, v44
	v_mul_f32_e32 v12, 0xbfb8aa3b, v12
	v_exp_f32_e32 v57, v12
	v_lshlrev_b32_e32 v12, 16, v45
	v_mul_f32_e32 v12, 0xbfb8aa3b, v12
	v_exp_f32_e32 v52, v12
	v_and_b32_e32 v12, 0xffff0000, v45
	v_mul_f32_e32 v12, 0xbfb8aa3b, v12
	v_exp_f32_e32 v53, v12
	v_lshlrev_b32_e32 v12, 16, v46
	v_mul_f32_e32 v12, 0xbfb8aa3b, v12
	v_exp_f32_e32 v44, v12
	v_and_b32_e32 v12, 0xffff0000, v46
	v_mul_f32_e32 v12, 0xbfb8aa3b, v12
	v_exp_f32_e32 v45, v12
	v_lshlrev_b32_e32 v12, 16, v47
	v_mul_f32_e32 v12, 0xbfb8aa3b, v12
	v_exp_f32_e32 v40, v12
	v_and_b32_e32 v12, 0xffff0000, v47
	v_rcp_f32_e32 v63, v39
	v_mul_f32_e32 v12, 0xbfb8aa3b, v12
	s_nop 0
	v_exp_f32_e32 v41, v12
	global_load_dwordx4 v[10:13], v[10:11], off
	v_pk_add_f32 v[50:51], v[50:51], 1.0 op_sel_hi:[1,0]
	v_fma_f32 v67, -v39, v63, 1.0
	v_fma_f32 v39, v67, v63, v63
	v_rcp_f32_e32 v63, v38
	s_nop 0
	v_add_u32_e32 v46, s2, v0
	ds_read_b128 v[46:49], v46
	s_add_i32 s2, s2, 0x8000
	v_fma_f32 v67, -v38, v63, 1.0
	v_fma_f32 v38, v67, v63, v63
	v_pk_fma_f32 v[34:35], v[38:39], v[34:35], 0 op_sel_hi:[1,1,0]
	s_waitcnt lgkmcnt(0)
	v_lshlrev_b32_e32 v54, 16, v46
	s_waitcnt vmcnt(2)
	v_and_b32_e32 v39, 0xffff0000, v2
	v_lshlrev_b32_e32 v38, 16, v2
	v_rcp_f32_e32 v2, v51
	s_nop 0
	v_and_b32_e32 v46, 0xffff0000, v46
	v_mul_f32_e32 v54, 0xbfb8aa3b, v54
	v_mul_f32_e32 v46, 0xbfb8aa3b, v46
	v_fma_f32 v66, -v51, v2, 1.0
	v_fma_f32 v51, v66, v2, v2
	v_rcp_f32_e32 v2, v50
	s_nop 0
	v_exp_f32_e32 v64, v54
	v_exp_f32_e32 v65, v46
	v_lshlrev_b32_e32 v46, 16, v47
	v_fma_f32 v66, -v50, v2, 1.0
	v_fma_f32 v50, v66, v2, v2
	v_pk_fma_f32 v[34:35], v[50:51], v[38:39], v[34:35]
	v_pk_add_f32 v[50:51], v[56:57], 1.0 op_sel_hi:[1,0]
	s_waitcnt vmcnt(1)
	v_and_b32_e32 v39, 0xffff0000, v6
	v_rcp_f32_e32 v2, v51
	v_lshlrev_b32_e32 v38, 16, v6
	s_nop 0
	v_mul_f32_e32 v46, 0xbfb8aa3b, v46
	v_exp_f32_e32 v58, v46
	v_and_b32_e32 v46, 0xffff0000, v47
	v_fma_f32 v56, -v51, v2, 1.0
	v_fma_f32 v51, v56, v2, v2
	v_rcp_f32_e32 v2, v50
	s_nop 0
	v_mul_f32_e32 v46, 0xbfb8aa3b, v46
	v_exp_f32_e32 v59, v46
	v_lshlrev_b32_e32 v46, 16, v48
	v_fma_f32 v56, -v50, v2, 1.0
	v_fma_f32 v50, v56, v2, v2
	v_pk_fma_f32 v[34:35], v[50:51], v[38:39], v[34:35]
	v_pk_add_f32 v[50:51], v[64:65], 1.0 op_sel_hi:[1,0]
	s_waitcnt vmcnt(0)
; DEVI float bfs(short h) { return __uint_as_float(((unsigned)(u16)h) << 16); }
; DEVI float sigm_f(float x) { return 1.f / (1.f + __expf(-x)); }
; DEVI void gemm256(const P& p, const u16* A, int lda, const u16* Bt, int ldb, int K, int brow, int bcol, int mode,
;                         int aux, int layer, int bmode) {
;     ...
;     for (int it = 0; it < 4; ++it) {
;       const int R = it * 64 + (tid >> 3), co = tid & 7;
;       const int row = brow + R, ocol = bcol + co * 8;
;       float sum[8] = {0, 0, 0, 0, 0, 0, 0, 0};
; #pragma unroll
;       for (int br = 0; br < 4; ++br) {
;         const int c = br * 8 + co;
;         bf16x8 g = *(const bf16x8*)(stg + R * 256 + SWZ(R, c) * 8);
;         float yb[8];
;         ld8((const u16*)(ws + O_YBR) + (size_t)row * 8192 + br * 2048 + ocol, yb);
; #pragma unroll
;         for (int e = 0; e < 8; ++e) sum[e] += (br == PROBE_ZB) ? 0.f : sigm_f(bfs(g[e])) * yb[e];
;       }
;       st8((u16*)(ws + O_ACC) + (size_t)row * 2048 + ocol, sum);
;     }
	v_and_b32_e32 v39, 0xffff0000, v10
	v_rcp_f32_e32 v2, v51
	s_nop 0
	v_lshlrev_b32_e32 v38, 16, v10
	v_mul_f32_e32 v46, 0xbfb8aa3b, v46
	v_exp_f32_e32 v54, v46
	v_fma_f32 v10, -v51, v2, 1.0
	v_fma_f32 v51, v10, v2, v2
	v_rcp_f32_e32 v2, v50
	s_nop 0
	v_and_b32_e32 v46, 0xffff0000, v48
	v_mul_f32_e32 v46, 0xbfb8aa3b, v46
	v_exp_f32_e32 v55, v46
	v_fma_f32 v10, -v50, v2, 1.0
	v_fma_f32 v50, v10, v2, v2
	v_rcp_f32_e32 v2, v33
	s_nop 0
	v_pk_fma_f32 v[34:35], v[50:51], v[38:39], v[34:35]
	v_lshlrev_b32_e32 v46, 16, v49
	v_and_b32_e32 v47, 0xffff0000, v49
	v_fma_f32 v10, -v33, v2, 1.0
	v_fma_f32 v33, v10, v2, v2
	v_rcp_f32_e32 v2, v32
	s_nop 0
	v_mul_f32_e32 v46, 0xbfb8aa3b, v46
	v_mul_f32_e32 v47, 0xbfb8aa3b, v47
	v_exp_f32_e32 v46, v46
	v_fma_f32 v10, -v32, v2, 1.0
	v_fma_f32 v32, v10, v2, v2
	v_pk_fma_f32 v[28:29], v[32:33], v[28:29], 0 op_sel_hi:[1,1,0]
	v_and_b32_e32 v33, 0xffff0000, v3
	v_lshlrev_b32_e32 v32, 16, v3
	v_pk_add_f32 v[2:3], v[42:43], 1.0 op_sel_hi:[1,0]
	v_exp_f32_e32 v47, v47
	v_rcp_f32_e32 v6, v3
	s_nop 0
	v_lshl_add_u64 v[48:49], v[16:17], 0, v[14:15]
	v_lshl_add_u64 v[16:17], v[16:17], 0, s[8:9]
	s_cmp_eq_u32 s2, 0x20000
	v_fma_f32 v38, -v3, v6, 1.0
	v_fma_f32 v3, v38, v6, v6
	v_rcp_f32_e32 v6, v2
	s_nop 0
	s_nop 0
	v_fma_f32 v38, -v2, v6, 1.0
	v_fma_f32 v2, v38, v6, v6
	v_pk_fma_f32 v[2:3], v[2:3], v[32:33], v[28:29]
	v_and_b32_e32 v29, 0xffff0000, v7
	v_lshlrev_b32_e32 v28, 16, v7
	v_pk_add_f32 v[6:7], v[52:53], 1.0 op_sel_hi:[1,0]
	s_nop 0
	v_rcp_f32_e32 v10, v7
	s_nop 0
	s_nop 0
	v_fma_f32 v33, -v7, v10, 1.0
	v_fma_f32 v7, v33, v10, v10
	v_rcp_f32_e32 v10, v6
	s_nop 0
	s_nop 0
	v_fma_f32 v33, -v6, v10, 1.0
	v_fma_f32 v6, v33, v10, v10
	v_pk_fma_f32 v[2:3], v[6:7], v[28:29], v[2:3]
	v_and_b32_e32 v7, 0xffff0000, v11
	v_lshlrev_b32_e32 v6, 16, v11
	v_pk_add_f32 v[10:11], v[58:59], 1.0 op_sel_hi:[1,0]
	s_nop 0
	v_rcp_f32_e32 v28, v11
	s_nop 0
	s_nop 0
	v_fma_f32 v32, -v11, v28, 1.0
	v_fma_f32 v11, v32, v28, v28
	v_rcp_f32_e32 v28, v10
	s_nop 0
	s_nop 0
	v_fma_f32 v32, -v10, v28, 1.0
	v_fma_f32 v10, v32, v28, v28
	v_pk_fma_f32 v[2:3], v[10:11], v[6:7], v[2:3]
	v_rcp_f32_e32 v6, v27
	s_nop 0
	s_nop 0
	v_fma_f32 v10, -v27, v6, 1.0
	v_fma_f32 v7, v10, v6, v6
	v_rcp_f32_e32 v6, v26
	s_nop 0
	s_nop 0
	v_fma_f32 v11, -v26, v6, 1.0
	v_fma_f32 v6, v11, v6, v6
	v_pk_fma_f32 v[6:7], v[6:7], v[24:25], 0 op_sel_hi:[1,1,0]
	v_pk_add_f32 v[24:25], v[36:37], 1.0 op_sel_hi:[1,0]
	v_and_b32_e32 v11, 0xffff0000, v4
	v_lshlrev_b32_e32 v10, 16, v4
	v_rcp_f32_e32 v4, v25
	s_nop 0
	s_nop 0
	v_fma_f32 v27, -v25, v4, 1.0
	v_fma_f32 v25, v27, v4, v4
	v_rcp_f32_e32 v4, v24
	s_nop 0
	s_nop 0
	v_fma_f32 v27, -v24, v4, 1.0
	v_fma_f32 v24, v27, v4, v4
	v_pk_fma_f32 v[6:7], v[24:25], v[10:11], v[6:7]
	v_pk_add_f32 v[24:25], v[44:45], 1.0 op_sel_hi:[1,0]
	v_and_b32_e32 v11, 0xffff0000, v8
	v_rcp_f32_e32 v4, v25
	v_lshlrev_b32_e32 v10, 16, v8
	s_nop 0
	s_nop 0
	v_fma_f32 v26, -v25, v4, 1.0
	v_fma_f32 v25, v26, v4, v4
	v_rcp_f32_e32 v4, v24
	s_nop 0
	s_nop 0
	v_fma_f32 v26, -v24, v4, 1.0
	v_fma_f32 v24, v26, v4, v4
	v_pk_fma_f32 v[6:7], v[24:25], v[10:11], v[6:7]
	v_pk_add_f32 v[24:25], v[54:55], 1.0 op_sel_hi:[1,0]
	v_and_b32_e32 v11, 0xffff0000, v12
	v_rcp_f32_e32 v4, v25
	s_nop 0
	v_lshlrev_b32_e32 v10, 16, v12
	v_fma_f32 v12, -v25, v4, 1.0
	v_fma_f32 v25, v12, v4, v4
	v_rcp_f32_e32 v4, v24
	s_nop 0
	s_nop 0
	v_fma_f32 v12, -v24, v4, 1.0
	v_fma_f32 v24, v12, v4, v4
	v_rcp_f32_e32 v4, v23
	s_nop 0
	v_pk_fma_f32 v[6:7], v[24:25], v[10:11], v[6:7]
	v_fma_f32 v10, -v23, v4, 1.0
	v_fma_f32 v11, v10, v4, v4
	v_rcp_f32_e32 v4, v22
	s_nop 0
	s_nop 0
	v_fma_f32 v10, -v22, v4, 1.0
	v_fma_f32 v10, v10, v4, v4
	v_pk_fma_f32 v[10:11], v[10:11], v[20:21], 0 op_sel_hi:[1,1,0]
	v_and_b32_e32 v21, 0xffff0000, v5
	v_lshlrev_b32_e32 v20, 16, v5
	v_pk_add_f32 v[4:5], v[30:31], 1.0 op_sel_hi:[1,0]
	s_nop 0
	v_rcp_f32_e32 v8, v5
	s_nop 0
	s_nop 0
	v_fma_f32 v22, -v5, v8, 1.0
	v_fma_f32 v5, v22, v8, v8
	v_rcp_f32_e32 v8, v4
	s_nop 0
	s_nop 0
	v_fma_f32 v22, -v4, v8, 1.0
	v_fma_f32 v4, v22, v8, v8
	v_pk_fma_f32 v[4:5], v[4:5], v[20:21], v[10:11]
	v_and_b32_e32 v11, 0xffff0000, v9
	v_lshlrev_b32_e32 v10, 16, v9
	v_pk_add_f32 v[8:9], v[40:41], 1.0 op_sel_hi:[1,0]
	s_nop 0
	v_rcp_f32_e32 v12, v9
	s_nop 0
	s_nop 0
	v_fma_f32 v21, -v9, v12, 1.0
	v_fma_f32 v9, v21, v12, v12
	v_rcp_f32_e32 v12, v8
	s_nop 0
	s_nop 0
	v_fma_f32 v21, -v8, v12, 1.0
	v_fma_f32 v8, v21, v12, v12
	v_pk_fma_f32 v[4:5], v[8:9], v[10:11], v[4:5]
	v_pk_add_f32 v[10:11], v[46:47], 1.0 op_sel_hi:[1,0]
	v_and_b32_e32 v9, 0xffff0000, v13
	v_rcp_f32_e32 v12, v11
	v_lshlrev_b32_e32 v8, 16, v13
	s_nop 0
	s_nop 0
	v_fma_f32 v20, -v11, v12, 1.0
	v_fma_f32 v11, v20, v12, v12
	v_rcp_f32_e32 v12, v10
	s_nop 0
	s_mov_b64 s[4:5], 0x100000
	v_lshl_add_u64 v[18:19], v[18:19], 0, s[4:5]
	v_fma_f32 v20, -v10, v12, 1.0
	v_fma_f32 v10, v20, v12, v12
	v_pk_fma_f32 v[4:5], v[10:11], v[8:9], v[4:5]
	v_bfe_u32 v10, v7, 16, 1
	v_bfe_u32 v8, v5, 16, 1
	v_bfe_u32 v9, v4, 16, 1
	v_bfe_u32 v11, v6, 16, 1
	v_bfe_u32 v12, v3, 16, 1
	v_bfe_u32 v13, v2, 16, 1
	v_bfe_u32 v20, v35, 16, 1
	v_bfe_u32 v21, v34, 16, 1
	v_add3_u32 v21, v34, v21, s33
	v_add3_u32 v20, v35, v20, s33
	v_add3_u32 v2, v2, v13, s33
	v_add3_u32 v3, v3, v12, s33
	v_add3_u32 v6, v6, v11, s33
	v_add3_u32 v7, v7, v10, s33
	v_add3_u32 v4, v4, v9, s33
	v_add3_u32 v5, v5, v8, s33
	v_perm_b32 v5, v5, v4, s27
	v_perm_b32 v4, v7, v6, s27
	v_perm_b32 v3, v3, v2, s27
	v_perm_b32 v2, v20, v21, s27
	global_store_dwordx4 v[48:49], v[2:5], off
	s_cbranch_scc0 .LBB0_315
	s_branch .LBB0_162
